# baseline (speedup 1.0000x reference)
; __device__ __forceinline__ void phase_rwkv_scan(const Params& p, int l, const int tidx) {
;     ...
;     for (int it = -1; it < NCH; it++) {
;       const int pc = it + 1;
;       if (pc < NCH) {
;         float* nbw = sbuf + (pc & 1) * BUFSZ;
;         float ur[TPW], uk[TPW], uv[TPW];
;         float m0, m5;
;         {
;           int tau0 = pc * RTC + pw * TPW;
;           int ta = dir ? (4095 - tau0 + 1) : (tau0 - 1);
;           int tb = dir ? (4095 - tau0 - TPW) : (tau0 + TPW);
;           m0 = (ta >= 0 && ta < SEQ) ? 1.f : 0.f;
;           m5 = (tb >= 0 && tb < SEQ) ? 1.f : 0.f;
;         }
.Lrp_loop:
	s_bitcmp1_b32 s0, 0
	s_cselect_b32 s11, 0xc100, 0
	s_lshl_b32 s12, s17, 11
	s_add_u32 s12, s12, s11
	v_add_u32_e32 v234, s12, v64
	v_add_u32_e32 v235, s12, v63
	v_add_u32_e32 v235, 0x6000, v235
	s_lshl_b32 s13, s17, 6
	s_add_u32 s13, s13, s11
	v_mov_b32_e32 v236, s13
	v_add_u32_e32 v237, 0xa000, v234
	s_cmpk_lt_i32 s0, 0x80
	s_cbranch_scc0 .Lrp_noprep
	s_cmpk_lt_i32 s0, 3
	s_cbranch_scc1 .Lrp_w0
	s_waitcnt vmcnt(16)
	s_branch .Lrp_w1

; __device__ __forceinline__ float bflo(unsigned w) { return __uint_as_float(w << 16); }
; __device__ __forceinline__ void phase_rwkv_scan(const Params& p, int l, const int tidx) {
;     ...
;       if (pc < NCH) {
;         float* nbw = sbuf + (pc & 1) * BUFSZ;
;         float ur[TPW], uk[TPW], uv[TPW];
;         float m0, m5;
;         {
;           int tau0 = pc * RTC + pw * TPW;
;           int ta = dir ? (4095 - tau0 + 1) : (tau0 - 1);
;           int tb = dir ? (4095 - tau0 - TPW) : (tau0 + TPW);
;           m0 = (ta >= 0 && ta < SEQ) ? 1.f : 0.f;
;           m5 = (tb >= 0 && tb < SEQ) ? 1.f : 0.f;
;         }
; #pragma unroll
;         for (int q = 0; q < TPW; q++) {
;           const int rr = 1 + q;
;           const float ma = (q == 0) ? m0 : 1.f, mb = (q == TPW - 1) ? m5 : 1.f;
;           float c0, nb;
;           c0 = bflo(raw[rr][0]); nb = 0.5f * (ma * bflo(raw[rr - 1][0]) + mb * bflo(raw[rr + 1][0])); ur[q] = c0 + mu_r * (nb - c0);
.Lrp_w1:
	s_or_b32 s12, s0, s17
	s_cmp_eq_u32 s12, 0
	s_cbranch_scc0 .Lrp_nb0
	v_mov_b32_e32 v70, 0
	v_mov_b32_e32 v80, 0
	v_mov_b32_e32 v90, 0
	v_mov_b32_e32 v100, 0
	v_mov_b32_e32 v110, 0
